# plain GEMM (out-proj/mlp1/mlp2) core switched from 32x32x16 to 16x16x32 bf16 MFMA shape (same tile, same LDS layout, M-half phases)
# speedup vs baseline: 1.1566x; 1.0087x over previous
; DI f32x16 zero16() { f32x16 z; for (int i = 0; i < 16; ++i) z[i] = 0.f; return z; }
; DI int opqv(int x) { asm volatile("" : "+v"(x)); return x; }
;   const int tid = opqv(threadIdx.x), lane = tid & 63, w = tid >> 6, wm = w >> 2, wn = w & 3, l32 = lane & 31, hf = lane >> 5;
;   f32x16 acc[2][2][2];
; #pragma unroll
;   for (int h = 0; h < 2; ++h)
; #pragma unroll
;     for (int i = 0; i < 2; ++i)
; #pragma unroll
;       for (int j = 0; j < 2; ++j) acc[h][i][j] = zero16();
;   const int nk = nk1 + nk2;
;   const int drow = lane >> 3, dslot = lane & 7, x7 = (l32 >> 1) & 7;
;     ...
;   if (V != 1) GLDS(0, 0);
;     ...
;   for (int lt = blockIdx.x >> 3; lt < 16 * nN; lt += gridDim.x >> 3) {
;     int mt, nt; tile_map(lt, 16, nN, 8, 4, mt, nt);
;     const int m0 = mt * 256, n0 = nt * 256;
.LBB0_871:
	s_lshl_b32 s29, s20, 4
	v_readlane_b32 s28, v253, 48
	v_readlane_b32 s30, v253, 50
	s_cmp_ge_u32 s28, s29
	s_cbranch_scc1 .LBB0_882
	s_add_u32 s12, s62, s12
	s_addc_u32 s13, s63, s13
	v_readlane_b32 s31, v251, 0
	s_lshr_b32 s34, s20, 3
	s_lshl_b32 s35, s8, 1
	s_lshl_b32 s36, s10, 1
	s_lshr_b32 s51, s50, 1
	s_sub_u32 s51, s51, 2
	s_and_b32 s31, s31, 7
	s_lshl_b32 s31, s31, 4
	v_lshrrev_b32_e32 v240, 6, v182
	v_and_b32_e32 v241, 63, v182
	v_readfirstlane_b32 s15, v240
	v_and_b32_e32 v242, 15, v241
	v_lshrrev_b32_e32 v243, 4, v241
	v_lshrrev_b32_e32 v244, 3, v241
	v_and_b32_e32 v245, 7, v241
	s_lshl_b32 s14, s15, 12
	s_add_u32 s14, s14, 32
	v_lshrrev_b32_e32 v246, 1, v244
	v_xor_b32_e32 v246, v245, v246
	v_lshlrev_b32_e32 v246, 4, v246
	s_lshl_b32 s53, s15, 2
	s_add_u32 s53, s53, 0
	s_lshl_b32 s53, s53, 3
	v_add_u32_e32 v247, s53, v244
	v_mad_u32_u24 v220, v247, s35, v246
	v_lshrrev_b32_e32 v246, 1, v244
	v_add_u32_e32 v246, 4, v246
	v_xor_b32_e32 v246, v245, v246
	v_lshlrev_b32_e32 v246, 4, v246
	s_lshl_b32 s53, s15, 2
	s_add_u32 s53, s53, 1
	s_lshl_b32 s53, s53, 3
	v_add_u32_e32 v247, s53, v244
	v_mad_u32_u24 v221, v247, s35, v246
	v_lshrrev_b32_e32 v246, 1, v244
	v_xor_b32_e32 v246, v245, v246
	v_lshlrev_b32_e32 v246, 4, v246
	s_lshl_b32 s53, s15, 2
	s_add_u32 s53, s53, 2
	s_lshl_b32 s53, s53, 3
	v_add_u32_e32 v247, s53, v244
	v_mad_u32_u24 v222, v247, s35, v246
	v_lshrrev_b32_e32 v246, 1, v244
	v_add_u32_e32 v246, 4, v246
	v_xor_b32_e32 v246, v245, v246
	v_lshlrev_b32_e32 v246, 4, v246
	s_lshl_b32 s53, s15, 2
	s_add_u32 s53, s53, 3
	s_lshl_b32 s53, s53, 3
	v_add_u32_e32 v247, s53, v244
	v_mad_u32_u24 v223, v247, s35, v246
	v_lshrrev_b32_e32 v246, 1, v242
	s_lshr_b32 s53, s15, 2
	s_and_b32 s54, s15, 3
	s_lshl_b32 s55, s53, 14
	s_add_u32 s55, s55, 32
	s_lshl_b32 s56, s54, 13
	s_add_u32 s56, s56, 0x8020
	v_lshlrev_b32_e32 v247, 7, v242
	v_add_u32_e32 v240, 0, v243
	v_xor_b32_e32 v240, v240, v246
	v_lshl_add_u32 v240, v240, 4, v247
	v_add_u32_e32 v204, s55, v240
	v_add_u32_e32 v208, s56, v240
	v_add_u32_e32 v206, 0x10000, v204
	v_add_u32_e32 v210, 0x10000, v208
	v_add_u32_e32 v240, 4, v243
	v_xor_b32_e32 v240, v240, v246
	v_lshl_add_u32 v240, v240, 4, v247
	v_add_u32_e32 v205, s55, v240
	v_add_u32_e32 v209, s56, v240
	v_add_u32_e32 v207, 0x10000, v205
	v_add_u32_e32 v211, 0x10000, v209
	s_add_u32 s40, s14, 0x10000
	v_and_b32_e32 v240, 1, v243
	v_lshlrev_b32_e32 v240, 3, v240
	v_add3_u32 v247, v247, v240, s40
	v_lshrrev_b32_e32 v240, 1, v243
	v_xor_b32_e32 v240, v240, v246
	v_mov_b32_e32 v178, v240
	v_xor_b32_e32 v179, 2, v240
	v_xor_b32_e32 v180, 4, v240
	v_xor_b32_e32 v181, 6, v240
	v_lshl_add_u32 v178, v178, 4, v247
	v_lshl_add_u32 v179, v179, 4, v247
	v_lshl_add_u32 v180, v180, 4, v247
	v_lshl_add_u32 v181, v181, 4, v247
	v_lshrrev_b32_e32 v240, 4, v241
	v_xor_b32_e32 v240, v245, v240
	v_lshlrev_b32_e32 v246, 7, v244
	v_add_u32_e32 v246, s40, v246
	v_lshl_add_u32 v194, v240, 4, v246
	v_xor_b32_e32 v240, 4, v240
	v_lshl_add_u32 v188, v240, 4, v246
	v_lshlrev_b32_e32 v195, 4, v245
	v_mad_u32_u24 v195, v244, s36, v195
	s_lshl_b32 s40, s36, 3
	s_lshl_b32 s58, s53, 7
	s_lshl_b32 s59, s54, 7
	s_mov_b32 s27, s28
	s_mov_b32 s26, 0
	s_lshr_b32 s53, s27, 5
	s_and_b32 s54, s27, 31
	s_lshr_b32 s55, s53, s34
	s_lshl_b32 s56, s55, s34
	s_sub_u32 s56, s53, s56
	s_lshl_b32 s55, s55, 3
	s_add_u32 s55, s55, s31
	s_lshr_b32 s57, s54, 2
	s_add_u32 s55, s55, s57
	s_lshl_b32 s56, s56, 2
	s_and_b32 s57, s54, 3
	s_add_u32 s56, s56, s57
	s_lshl_b32 s57, s55, 8
	s_mul_i32 s57, s57, s35
	s_add_u32 s22, s0, s57
	s_addc_u32 s23, s1, 0
	s_lshl_b32 s57, s56, 8
	s_mul_i32 s57, s57, s35
	s_add_u32 s24, s6, s57
	s_addc_u32 s25, s7, 0
	s_add_u32 m0, s14, 0x0
	s_nop 0
	global_load_lds_dwordx4 v220, s[22:23]
	s_add_u32 m0, s14, 0x8000
	s_nop 0
	global_load_lds_dwordx4 v220, s[24:25]
	s_add_u32 m0, s14, 0x400
	s_nop 0
	global_load_lds_dwordx4 v221, s[22:23]
	s_add_u32 m0, s14, 0x8400
	s_nop 0
	global_load_lds_dwordx4 v221, s[24:25]
	s_add_u32 m0, s14, 0x800
	s_nop 0
	global_load_lds_dwordx4 v222, s[22:23]
	s_add_u32 m0, s14, 0x8800
	s_nop 0
	global_load_lds_dwordx4 v222, s[24:25]
	s_add_u32 m0, s14, 0xc00
	s_nop 0
	global_load_lds_dwordx4 v223, s[22:23]
	s_add_u32 m0, s14, 0x8c00
	s_nop 0
	global_load_lds_dwordx4 v223, s[24:25]
	s_add_u32 s22, s22, 0x80
	s_addc_u32 s23, s23, 0
	s_add_u32 s24, s24, 0x80
	s_addc_u32 s25, s25, 0
	s_add_u32 s26, s26, 1
	s_cmp_eq_u32 s26, s50
	s_cbranch_scc0 .Lgm_cadv_done1
	s_mov_b32 s26, 0
	s_add_u32 s27, s27, s30
	s_cmp_lt_u32 s27, s29
	s_cbranch_scc1 .Lgm_cadv_new1
	s_lshl_b32 s53, s50, 7
	s_sub_u32 s22, s22, s53
	s_subb_u32 s23, s23, 0
	s_sub_u32 s24, s24, s53
	s_subb_u32 s25, s25, 0
	s_branch .Lgm_cadv_done1

; #define RAWBAR() { asm volatile("s_waitcnt vmcnt(0) lgkmcnt(0)" ::: "memory"); __builtin_amdgcn_s_barrier(); }
;     ...
;   if (V != 1) GLDS(0, 0);
;   RAWBAR();
;   for (int kt = 0; kt < nk; kt += 2) {
;     if (V != 1) GLDS(kt + 1, 1);
;     if (V != 2) COMPUTE(0);
;     RAWBAR();
;     if (V != 1) if (kt + 2 < nk) GLDS(kt + 2, 0);
;     if (V != 2) COMPUTE(1);
;     RAWBAR();
.Lgm_cadv_done2:
	s_waitcnt vmcnt(8)
	s_barrier
	ds_read_b128 v[128:131], v204
	ds_read_b128 v[132:135], v204 offset:2048
	ds_read_b128 v[136:139], v204 offset:4096
	ds_read_b128 v[140:143], v204 offset:6144
	ds_read_b128 v[162:165], v208
	ds_read_b128 v[166:169], v208 offset:2048
	ds_read_b128 v[170:173], v208 offset:4096
	ds_read_b128 v[174:177], v208 offset:6144
	ds_read_b128 v[144:147], v204 offset:8192
	ds_read_b128 v[148:151], v204 offset:10240
	ds_read_b128 v[152:155], v204 offset:12288
	ds_read_b128 v[156:159], v204 offset:14336
	ds_read_b128 v[224:227], v209
	ds_read_b128 v[228:231], v209 offset:2048
	ds_read_b128 v[232:235], v209 offset:4096
	ds_read_b128 v[236:239], v209 offset:6144
.Lgm_tile:
	s_waitcnt lgkmcnt(8)
	v_mfma_f32_16x16x32_bf16 v[0:3], v[162:165], v[128:131], 0
	v_mfma_f32_16x16x32_bf16 v[4:7], v[166:169], v[128:131], 0
	v_mfma_f32_16x16x32_bf16 v[8:11], v[170:173], v[128:131], 0
	v_mfma_f32_16x16x32_bf16 v[12:15], v[174:177], v[128:131], 0
	ds_read_b128 v[128:131], v205
	v_mfma_f32_16x16x32_bf16 v[16:19], v[162:165], v[132:135], 0
	v_mfma_f32_16x16x32_bf16 v[20:23], v[166:169], v[132:135], 0
	v_mfma_f32_16x16x32_bf16 v[24:27], v[170:173], v[132:135], 0
	v_mfma_f32_16x16x32_bf16 v[28:31], v[174:177], v[132:135], 0
	ds_read_b128 v[132:135], v205 offset:2048
	v_mfma_f32_16x16x32_bf16 v[32:35], v[162:165], v[136:139], 0
	v_mfma_f32_16x16x32_bf16 v[36:39], v[166:169], v[136:139], 0
	v_mfma_f32_16x16x32_bf16 v[40:43], v[170:173], v[136:139], 0
	v_mfma_f32_16x16x32_bf16 v[44:47], v[174:177], v[136:139], 0
	ds_read_b128 v[136:139], v205 offset:4096
	v_mfma_f32_16x16x32_bf16 v[48:51], v[162:165], v[140:143], 0
	v_mfma_f32_16x16x32_bf16 v[52:55], v[166:169], v[140:143], 0
	v_mfma_f32_16x16x32_bf16 v[56:59], v[170:173], v[140:143], 0
	v_mfma_f32_16x16x32_bf16 v[60:63], v[174:177], v[140:143], 0
	ds_read_b128 v[140:143], v205 offset:6144
	s_waitcnt lgkmcnt(8)
	v_mfma_f32_16x16x32_bf16 v[64:67], v[162:165], v[144:147], 0
	v_mfma_f32_16x16x32_bf16 v[68:71], v[166:169], v[144:147], 0
	v_mfma_f32_16x16x32_bf16 v[72:75], v[170:173], v[144:147], 0
	v_mfma_f32_16x16x32_bf16 v[76:79], v[174:177], v[144:147], 0
	ds_read_b128 v[144:147], v205 offset:8192
	v_mfma_f32_16x16x32_bf16 v[80:83], v[162:165], v[148:151], 0
	v_mfma_f32_16x16x32_bf16 v[84:87], v[166:169], v[148:151], 0
	v_mfma_f32_16x16x32_bf16 v[88:91], v[170:173], v[148:151], 0
	v_mfma_f32_16x16x32_bf16 v[92:95], v[174:177], v[148:151], 0
	ds_read_b128 v[148:151], v205 offset:10240
	v_mfma_f32_16x16x32_bf16 v[96:99], v[162:165], v[152:155], 0
	v_mfma_f32_16x16x32_bf16 v[100:103], v[166:169], v[152:155], 0
	v_mfma_f32_16x16x32_bf16 v[104:107], v[170:173], v[152:155], 0
	v_mfma_f32_16x16x32_bf16 v[108:111], v[174:177], v[152:155], 0
	ds_read_b128 v[152:155], v205 offset:12288
	v_mfma_f32_16x16x32_bf16 v[112:115], v[162:165], v[156:159], 0
	v_mfma_f32_16x16x32_bf16 v[116:119], v[166:169], v[156:159], 0
	v_mfma_f32_16x16x32_bf16 v[120:123], v[170:173], v[156:159], 0
	v_mfma_f32_16x16x32_bf16 v[124:127], v[174:177], v[156:159], 0
	ds_read_b128 v[156:159], v205 offset:14336
	s_waitcnt vmcnt(0) lgkmcnt(0)
	s_barrier
	ds_read_b128 v[162:165], v210
	ds_read_b128 v[166:169], v210 offset:2048
	ds_read_b128 v[170:173], v210 offset:4096
	ds_read_b128 v[174:177], v210 offset:6144
	s_add_u32 m0, s14, 0x0
	v_mfma_f32_16x16x32_bf16 v[0:3], v[224:227], v[128:131], v[0:3]
	global_load_lds_dwordx4 v220, s[22:23]
	v_mfma_f32_16x16x32_bf16 v[4:7], v[228:231], v[128:131], v[4:7]
	s_add_u32 m0, s14, 0x8000
	v_mfma_f32_16x16x32_bf16 v[8:11], v[232:235], v[128:131], v[8:11]
	global_load_lds_dwordx4 v220, s[24:25]
	v_mfma_f32_16x16x32_bf16 v[12:15], v[236:239], v[128:131], v[12:15]
	ds_read_b128 v[128:131], v206
	s_add_u32 m0, s14, 0x400
	v_mfma_f32_16x16x32_bf16 v[16:19], v[224:227], v[132:135], v[16:19]
	global_load_lds_dwordx4 v221, s[22:23]
	v_mfma_f32_16x16x32_bf16 v[20:23], v[228:231], v[132:135], v[20:23]
	s_add_u32 m0, s14, 0x8400
	v_mfma_f32_16x16x32_bf16 v[24:27], v[232:235], v[132:135], v[24:27]
	global_load_lds_dwordx4 v221, s[24:25]
	v_mfma_f32_16x16x32_bf16 v[28:31], v[236:239], v[132:135], v[28:31]
	ds_read_b128 v[132:135], v206 offset:2048
	s_add_u32 m0, s14, 0x800
	v_mfma_f32_16x16x32_bf16 v[32:35], v[224:227], v[136:139], v[32:35]
	global_load_lds_dwordx4 v222, s[22:23]
	v_mfma_f32_16x16x32_bf16 v[36:39], v[228:231], v[136:139], v[36:39]
	s_add_u32 m0, s14, 0x8800
	v_mfma_f32_16x16x32_bf16 v[40:43], v[232:235], v[136:139], v[40:43]
	global_load_lds_dwordx4 v222, s[24:25]
	v_mfma_f32_16x16x32_bf16 v[44:47], v[236:239], v[136:139], v[44:47]
	ds_read_b128 v[136:139], v206 offset:4096
	s_add_u32 m0, s14, 0xc00
	v_mfma_f32_16x16x32_bf16 v[48:51], v[224:227], v[140:143], v[48:51]
	global_load_lds_dwordx4 v223, s[22:23]
	v_mfma_f32_16x16x32_bf16 v[52:55], v[228:231], v[140:143], v[52:55]
	s_add_u32 m0, s14, 0x8c00
	v_mfma_f32_16x16x32_bf16 v[56:59], v[232:235], v[140:143], v[56:59]
	global_load_lds_dwordx4 v223, s[24:25]
	v_mfma_f32_16x16x32_bf16 v[60:63], v[236:239], v[140:143], v[60:63]
	ds_read_b128 v[140:143], v206 offset:6144
	v_mfma_f32_16x16x32_bf16 v[64:67], v[224:227], v[144:147], v[64:67]
	v_mfma_f32_16x16x32_bf16 v[68:71], v[228:231], v[144:147], v[68:71]
	v_mfma_f32_16x16x32_bf16 v[72:75], v[232:235], v[144:147], v[72:75]
	v_mfma_f32_16x16x32_bf16 v[76:79], v[236:239], v[144:147], v[76:79]
	ds_read_b128 v[144:147], v206 offset:8192
	v_mfma_f32_16x16x32_bf16 v[80:83], v[224:227], v[148:151], v[80:83]
	v_mfma_f32_16x16x32_bf16 v[84:87], v[228:231], v[148:151], v[84:87]
	v_mfma_f32_16x16x32_bf16 v[88:91], v[232:235], v[148:151], v[88:91]
	v_mfma_f32_16x16x32_bf16 v[92:95], v[236:239], v[148:151], v[92:95]
	ds_read_b128 v[148:151], v206 offset:10240
	v_mfma_f32_16x16x32_bf16 v[96:99], v[224:227], v[152:155], v[96:99]
	v_mfma_f32_16x16x32_bf16 v[100:103], v[228:231], v[152:155], v[100:103]
	v_mfma_f32_16x16x32_bf16 v[104:107], v[232:235], v[152:155], v[104:107]
	v_mfma_f32_16x16x32_bf16 v[108:111], v[236:239], v[152:155], v[108:111]
	ds_read_b128 v[152:155], v206 offset:12288
	v_mfma_f32_16x16x32_bf16 v[112:115], v[224:227], v[156:159], v[112:115]
	v_mfma_f32_16x16x32_bf16 v[116:119], v[228:231], v[156:159], v[116:119]
	v_mfma_f32_16x16x32_bf16 v[120:123], v[232:235], v[156:159], v[120:123]
	v_mfma_f32_16x16x32_bf16 v[124:127], v[236:239], v[156:159], v[124:127]
	ds_read_b128 v[156:159], v206 offset:14336
	ds_read_b128 v[224:227], v211
	ds_read_b128 v[228:231], v211 offset:2048
	ds_read_b128 v[232:235], v211 offset:4096
	ds_read_b128 v[236:239], v211 offset:6144
	s_add_u32 s22, s22, 0x80
	s_addc_u32 s23, s23, 0
	s_add_u32 s24, s24, 0x80
	s_addc_u32 s25, s25, 0
	s_add_u32 s26, s26, 1
	s_cmp_eq_u32 s26, s50
	s_cbranch_scc0 .Lgm_cadv_done3
	s_mov_b32 s26, 0
	s_add_u32 s27, s27, s30
	s_cmp_lt_u32 s27, s29
	s_cbranch_scc1 .Lgm_cadv_new3
	s_lshl_b32 s53, s50, 7
	s_sub_u32 s22, s22, s53
	s_subb_u32 s23, s23, 0
	s_sub_u32 s24, s24, s53
	s_subb_u32 s25, s25, 0
	s_branch .Lgm_cadv_done3

; #define RAWBAR() { asm volatile("s_waitcnt vmcnt(0) lgkmcnt(0)" ::: "memory"); __builtin_amdgcn_s_barrier(); }
;     ...
;   if (V != 1) GLDS(0, 0);
;   RAWBAR();
;   for (int kt = 0; kt < nk; kt += 2) {
;     if (V != 1) GLDS(kt + 1, 1);
;     if (V != 2) COMPUTE(0);
;     RAWBAR();
;     if (V != 1) if (kt + 2 < nk) GLDS(kt + 2, 0);
;     if (V != 2) COMPUTE(1);
;     RAWBAR();
.Lgm_cadv_done3:
	s_waitcnt lgkmcnt(8)
	v_mfma_f32_16x16x32_bf16 v[0:3], v[162:165], v[128:131], v[0:3]
	v_mfma_f32_16x16x32_bf16 v[4:7], v[166:169], v[128:131], v[4:7]
	v_mfma_f32_16x16x32_bf16 v[8:11], v[170:173], v[128:131], v[8:11]
	v_mfma_f32_16x16x32_bf16 v[12:15], v[174:177], v[128:131], v[12:15]
	ds_read_b128 v[128:131], v207
	v_mfma_f32_16x16x32_bf16 v[16:19], v[162:165], v[132:135], v[16:19]
	v_mfma_f32_16x16x32_bf16 v[20:23], v[166:169], v[132:135], v[20:23]
	v_mfma_f32_16x16x32_bf16 v[24:27], v[170:173], v[132:135], v[24:27]
	v_mfma_f32_16x16x32_bf16 v[28:31], v[174:177], v[132:135], v[28:31]
	ds_read_b128 v[132:135], v207 offset:2048
	v_mfma_f32_16x16x32_bf16 v[32:35], v[162:165], v[136:139], v[32:35]
	v_mfma_f32_16x16x32_bf16 v[36:39], v[166:169], v[136:139], v[36:39]
	v_mfma_f32_16x16x32_bf16 v[40:43], v[170:173], v[136:139], v[40:43]
	v_mfma_f32_16x16x32_bf16 v[44:47], v[174:177], v[136:139], v[44:47]
	ds_read_b128 v[136:139], v207 offset:4096
	v_mfma_f32_16x16x32_bf16 v[48:51], v[162:165], v[140:143], v[48:51]
	v_mfma_f32_16x16x32_bf16 v[52:55], v[166:169], v[140:143], v[52:55]
	v_mfma_f32_16x16x32_bf16 v[56:59], v[170:173], v[140:143], v[56:59]
	v_mfma_f32_16x16x32_bf16 v[60:63], v[174:177], v[140:143], v[60:63]
	ds_read_b128 v[140:143], v207 offset:6144
	s_waitcnt lgkmcnt(8)
	v_mfma_f32_16x16x32_bf16 v[64:67], v[162:165], v[144:147], v[64:67]
	v_mfma_f32_16x16x32_bf16 v[68:71], v[166:169], v[144:147], v[68:71]
	v_mfma_f32_16x16x32_bf16 v[72:75], v[170:173], v[144:147], v[72:75]
	v_mfma_f32_16x16x32_bf16 v[76:79], v[174:177], v[144:147], v[76:79]
	ds_read_b128 v[144:147], v207 offset:8192
	v_mfma_f32_16x16x32_bf16 v[80:83], v[162:165], v[148:151], v[80:83]
	v_mfma_f32_16x16x32_bf16 v[84:87], v[166:169], v[148:151], v[84:87]
	v_mfma_f32_16x16x32_bf16 v[88:91], v[170:173], v[148:151], v[88:91]
	v_mfma_f32_16x16x32_bf16 v[92:95], v[174:177], v[148:151], v[92:95]
	ds_read_b128 v[148:151], v207 offset:10240
	v_mfma_f32_16x16x32_bf16 v[96:99], v[162:165], v[152:155], v[96:99]
	v_mfma_f32_16x16x32_bf16 v[100:103], v[166:169], v[152:155], v[100:103]
	v_mfma_f32_16x16x32_bf16 v[104:107], v[170:173], v[152:155], v[104:107]
	v_mfma_f32_16x16x32_bf16 v[108:111], v[174:177], v[152:155], v[108:111]
	ds_read_b128 v[152:155], v207 offset:12288
	v_mfma_f32_16x16x32_bf16 v[112:115], v[162:165], v[156:159], v[112:115]
	v_mfma_f32_16x16x32_bf16 v[116:119], v[166:169], v[156:159], v[116:119]
	v_mfma_f32_16x16x32_bf16 v[120:123], v[170:173], v[156:159], v[120:123]
	v_mfma_f32_16x16x32_bf16 v[124:127], v[174:177], v[156:159], v[124:127]
	ds_read_b128 v[156:159], v207 offset:14336
	s_waitcnt vmcnt(0) lgkmcnt(0)
	s_barrier
	ds_read_b128 v[162:165], v208
	ds_read_b128 v[166:169], v208 offset:2048
	ds_read_b128 v[170:173], v208 offset:4096
	ds_read_b128 v[174:177], v208 offset:6144
	s_add_u32 m0, s14, 0x10000
	v_mfma_f32_16x16x32_bf16 v[0:3], v[224:227], v[128:131], v[0:3]
	global_load_lds_dwordx4 v220, s[22:23]
	v_mfma_f32_16x16x32_bf16 v[4:7], v[228:231], v[128:131], v[4:7]
	s_add_u32 m0, s14, 0x18000
	v_mfma_f32_16x16x32_bf16 v[8:11], v[232:235], v[128:131], v[8:11]
	global_load_lds_dwordx4 v220, s[24:25]
	v_mfma_f32_16x16x32_bf16 v[12:15], v[236:239], v[128:131], v[12:15]
	ds_read_b128 v[128:131], v204
	s_add_u32 m0, s14, 0x10400
	v_mfma_f32_16x16x32_bf16 v[16:19], v[224:227], v[132:135], v[16:19]
	global_load_lds_dwordx4 v221, s[22:23]
	v_mfma_f32_16x16x32_bf16 v[20:23], v[228:231], v[132:135], v[20:23]
	s_add_u32 m0, s14, 0x18400
	v_mfma_f32_16x16x32_bf16 v[24:27], v[232:235], v[132:135], v[24:27]
	global_load_lds_dwordx4 v221, s[24:25]
	v_mfma_f32_16x16x32_bf16 v[28:31], v[236:239], v[132:135], v[28:31]
	ds_read_b128 v[132:135], v204 offset:2048
	s_add_u32 m0, s14, 0x10800
	v_mfma_f32_16x16x32_bf16 v[32:35], v[224:227], v[136:139], v[32:35]
	global_load_lds_dwordx4 v222, s[22:23]
	v_mfma_f32_16x16x32_bf16 v[36:39], v[228:231], v[136:139], v[36:39]
	s_add_u32 m0, s14, 0x18800
	v_mfma_f32_16x16x32_bf16 v[40:43], v[232:235], v[136:139], v[40:43]
	global_load_lds_dwordx4 v222, s[24:25]
	v_mfma_f32_16x16x32_bf16 v[44:47], v[236:239], v[136:139], v[44:47]
	ds_read_b128 v[136:139], v204 offset:4096
	s_add_u32 m0, s14, 0x10c00
	v_mfma_f32_16x16x32_bf16 v[48:51], v[224:227], v[140:143], v[48:51]
	global_load_lds_dwordx4 v223, s[22:23]
	v_mfma_f32_16x16x32_bf16 v[52:55], v[228:231], v[140:143], v[52:55]
	s_add_u32 m0, s14, 0x18c00
	v_mfma_f32_16x16x32_bf16 v[56:59], v[232:235], v[140:143], v[56:59]
	global_load_lds_dwordx4 v223, s[24:25]
	v_mfma_f32_16x16x32_bf16 v[60:63], v[236:239], v[140:143], v[60:63]
	ds_read_b128 v[140:143], v204 offset:6144
	v_mfma_f32_16x16x32_bf16 v[64:67], v[224:227], v[144:147], v[64:67]
	v_mfma_f32_16x16x32_bf16 v[68:71], v[228:231], v[144:147], v[68:71]
	v_mfma_f32_16x16x32_bf16 v[72:75], v[232:235], v[144:147], v[72:75]
	v_mfma_f32_16x16x32_bf16 v[76:79], v[236:239], v[144:147], v[76:79]
	ds_read_b128 v[144:147], v204 offset:8192
	v_mfma_f32_16x16x32_bf16 v[80:83], v[224:227], v[148:151], v[80:83]
	v_mfma_f32_16x16x32_bf16 v[84:87], v[228:231], v[148:151], v[84:87]
	v_mfma_f32_16x16x32_bf16 v[88:91], v[232:235], v[148:151], v[88:91]
	v_mfma_f32_16x16x32_bf16 v[92:95], v[236:239], v[148:151], v[92:95]
	ds_read_b128 v[148:151], v204 offset:10240
	v_mfma_f32_16x16x32_bf16 v[96:99], v[224:227], v[152:155], v[96:99]
	v_mfma_f32_16x16x32_bf16 v[100:103], v[228:231], v[152:155], v[100:103]
	v_mfma_f32_16x16x32_bf16 v[104:107], v[232:235], v[152:155], v[104:107]
	v_mfma_f32_16x16x32_bf16 v[108:111], v[236:239], v[152:155], v[108:111]
	ds_read_b128 v[152:155], v204 offset:12288
	v_mfma_f32_16x16x32_bf16 v[112:115], v[224:227], v[156:159], v[112:115]
	v_mfma_f32_16x16x32_bf16 v[116:119], v[228:231], v[156:159], v[116:119]
	v_mfma_f32_16x16x32_bf16 v[120:123], v[232:235], v[156:159], v[120:123]
	v_mfma_f32_16x16x32_bf16 v[124:127], v[236:239], v[156:159], v[124:127]
	ds_read_b128 v[156:159], v204 offset:14336
	ds_read_b128 v[224:227], v209
	ds_read_b128 v[228:231], v209 offset:2048
	ds_read_b128 v[232:235], v209 offset:4096
	ds_read_b128 v[236:239], v209 offset:6144
	s_add_u32 s22, s22, 0x80
	s_addc_u32 s23, s23, 0
	s_add_u32 s24, s24, 0x80
	s_addc_u32 s25, s25, 0
	s_add_u32 s26, s26, 1
	s_cmp_eq_u32 s26, s50
	s_cbranch_scc0 .Lgm_cadv_done4
	s_mov_b32 s26, 0
	s_add_u32 s27, s27, s30
	s_cmp_lt_u32 s27, s29
	s_cbranch_scc1 .Lgm_cadv_new4
	s_lshl_b32 s53, s50, 7
	s_sub_u32 s22, s22, s53
	s_subb_u32 s23, s23, 0
	s_sub_u32 s24, s24, s53
	s_subb_u32 s25, s25, 0
	s_branch .Lgm_cadv_done4

; #define RAWBAR() { asm volatile("s_waitcnt vmcnt(0) lgkmcnt(0)" ::: "memory"); __builtin_amdgcn_s_barrier(); }
;     ...
;   if (V != 1) GLDS(0, 0);
;   RAWBAR();
;   for (int kt = 0; kt < nk; kt += 2) {
;     if (V != 1) GLDS(kt + 1, 1);
;     if (V != 2) COMPUTE(0);
;     RAWBAR();
;     if (V != 1) if (kt + 2 < nk) GLDS(kt + 2, 0);
;     if (V != 2) COMPUTE(1);
;     RAWBAR();
.Lgm_pair:
	s_waitcnt lgkmcnt(8)
	v_mfma_f32_16x16x32_bf16 v[0:3], v[162:165], v[128:131], v[0:3]
	v_mfma_f32_16x16x32_bf16 v[4:7], v[166:169], v[128:131], v[4:7]
	v_mfma_f32_16x16x32_bf16 v[8:11], v[170:173], v[128:131], v[8:11]
	v_mfma_f32_16x16x32_bf16 v[12:15], v[174:177], v[128:131], v[12:15]
	ds_read_b128 v[128:131], v205
	v_mfma_f32_16x16x32_bf16 v[16:19], v[162:165], v[132:135], v[16:19]
	v_mfma_f32_16x16x32_bf16 v[20:23], v[166:169], v[132:135], v[20:23]
	v_mfma_f32_16x16x32_bf16 v[24:27], v[170:173], v[132:135], v[24:27]
	v_mfma_f32_16x16x32_bf16 v[28:31], v[174:177], v[132:135], v[28:31]
	ds_read_b128 v[132:135], v205 offset:2048
	v_mfma_f32_16x16x32_bf16 v[32:35], v[162:165], v[136:139], v[32:35]
	v_mfma_f32_16x16x32_bf16 v[36:39], v[166:169], v[136:139], v[36:39]
	v_mfma_f32_16x16x32_bf16 v[40:43], v[170:173], v[136:139], v[40:43]
	v_mfma_f32_16x16x32_bf16 v[44:47], v[174:177], v[136:139], v[44:47]
	ds_read_b128 v[136:139], v205 offset:4096
	v_mfma_f32_16x16x32_bf16 v[48:51], v[162:165], v[140:143], v[48:51]
	v_mfma_f32_16x16x32_bf16 v[52:55], v[166:169], v[140:143], v[52:55]
	v_mfma_f32_16x16x32_bf16 v[56:59], v[170:173], v[140:143], v[56:59]
	v_mfma_f32_16x16x32_bf16 v[60:63], v[174:177], v[140:143], v[60:63]
	ds_read_b128 v[140:143], v205 offset:6144
	s_waitcnt lgkmcnt(8)
	v_mfma_f32_16x16x32_bf16 v[64:67], v[162:165], v[144:147], v[64:67]
	v_mfma_f32_16x16x32_bf16 v[68:71], v[166:169], v[144:147], v[68:71]
	v_mfma_f32_16x16x32_bf16 v[72:75], v[170:173], v[144:147], v[72:75]
	v_mfma_f32_16x16x32_bf16 v[76:79], v[174:177], v[144:147], v[76:79]
	ds_read_b128 v[144:147], v205 offset:8192
	v_mfma_f32_16x16x32_bf16 v[80:83], v[162:165], v[148:151], v[80:83]
	v_mfma_f32_16x16x32_bf16 v[84:87], v[166:169], v[148:151], v[84:87]
	v_mfma_f32_16x16x32_bf16 v[88:91], v[170:173], v[148:151], v[88:91]
	v_mfma_f32_16x16x32_bf16 v[92:95], v[174:177], v[148:151], v[92:95]
	ds_read_b128 v[148:151], v205 offset:10240
	v_mfma_f32_16x16x32_bf16 v[96:99], v[162:165], v[152:155], v[96:99]
	v_mfma_f32_16x16x32_bf16 v[100:103], v[166:169], v[152:155], v[100:103]
	v_mfma_f32_16x16x32_bf16 v[104:107], v[170:173], v[152:155], v[104:107]
	v_mfma_f32_16x16x32_bf16 v[108:111], v[174:177], v[152:155], v[108:111]
	ds_read_b128 v[152:155], v205 offset:12288
	v_mfma_f32_16x16x32_bf16 v[112:115], v[162:165], v[156:159], v[112:115]
	v_mfma_f32_16x16x32_bf16 v[116:119], v[166:169], v[156:159], v[116:119]
	v_mfma_f32_16x16x32_bf16 v[120:123], v[170:173], v[156:159], v[120:123]
	v_mfma_f32_16x16x32_bf16 v[124:127], v[174:177], v[156:159], v[124:127]
	ds_read_b128 v[156:159], v205 offset:14336
	s_waitcnt vmcnt(0) lgkmcnt(0)
	s_barrier
	ds_read_b128 v[162:165], v210
	ds_read_b128 v[166:169], v210 offset:2048
	ds_read_b128 v[170:173], v210 offset:4096
	ds_read_b128 v[174:177], v210 offset:6144
	s_add_u32 m0, s14, 0x0
	v_mfma_f32_16x16x32_bf16 v[0:3], v[224:227], v[128:131], v[0:3]
	global_load_lds_dwordx4 v220, s[22:23]
	v_mfma_f32_16x16x32_bf16 v[4:7], v[228:231], v[128:131], v[4:7]
	s_add_u32 m0, s14, 0x8000
	v_mfma_f32_16x16x32_bf16 v[8:11], v[232:235], v[128:131], v[8:11]
	global_load_lds_dwordx4 v220, s[24:25]
	v_mfma_f32_16x16x32_bf16 v[12:15], v[236:239], v[128:131], v[12:15]
	ds_read_b128 v[128:131], v206
	s_add_u32 m0, s14, 0x400
	v_mfma_f32_16x16x32_bf16 v[16:19], v[224:227], v[132:135], v[16:19]
	global_load_lds_dwordx4 v221, s[22:23]
	v_mfma_f32_16x16x32_bf16 v[20:23], v[228:231], v[132:135], v[20:23]
	s_add_u32 m0, s14, 0x8400
	v_mfma_f32_16x16x32_bf16 v[24:27], v[232:235], v[132:135], v[24:27]
	global_load_lds_dwordx4 v221, s[24:25]
	v_mfma_f32_16x16x32_bf16 v[28:31], v[236:239], v[132:135], v[28:31]
	ds_read_b128 v[132:135], v206 offset:2048
	s_add_u32 m0, s14, 0x800
	v_mfma_f32_16x16x32_bf16 v[32:35], v[224:227], v[136:139], v[32:35]
	global_load_lds_dwordx4 v222, s[22:23]
	v_mfma_f32_16x16x32_bf16 v[36:39], v[228:231], v[136:139], v[36:39]
	s_add_u32 m0, s14, 0x8800
	v_mfma_f32_16x16x32_bf16 v[40:43], v[232:235], v[136:139], v[40:43]
	global_load_lds_dwordx4 v222, s[24:25]
	v_mfma_f32_16x16x32_bf16 v[44:47], v[236:239], v[136:139], v[44:47]
	ds_read_b128 v[136:139], v206 offset:4096
	s_add_u32 m0, s14, 0xc00
	v_mfma_f32_16x16x32_bf16 v[48:51], v[224:227], v[140:143], v[48:51]
	global_load_lds_dwordx4 v223, s[22:23]
	v_mfma_f32_16x16x32_bf16 v[52:55], v[228:231], v[140:143], v[52:55]
	s_add_u32 m0, s14, 0x8c00
	v_mfma_f32_16x16x32_bf16 v[56:59], v[232:235], v[140:143], v[56:59]
	global_load_lds_dwordx4 v223, s[24:25]
	v_mfma_f32_16x16x32_bf16 v[60:63], v[236:239], v[140:143], v[60:63]
	ds_read_b128 v[140:143], v206 offset:6144
	v_mfma_f32_16x16x32_bf16 v[64:67], v[224:227], v[144:147], v[64:67]
	v_mfma_f32_16x16x32_bf16 v[68:71], v[228:231], v[144:147], v[68:71]
	v_mfma_f32_16x16x32_bf16 v[72:75], v[232:235], v[144:147], v[72:75]
	v_mfma_f32_16x16x32_bf16 v[76:79], v[236:239], v[144:147], v[76:79]
	ds_read_b128 v[144:147], v206 offset:8192
	v_mfma_f32_16x16x32_bf16 v[80:83], v[224:227], v[148:151], v[80:83]
	v_mfma_f32_16x16x32_bf16 v[84:87], v[228:231], v[148:151], v[84:87]
	v_mfma_f32_16x16x32_bf16 v[88:91], v[232:235], v[148:151], v[88:91]
	v_mfma_f32_16x16x32_bf16 v[92:95], v[236:239], v[148:151], v[92:95]
	ds_read_b128 v[148:151], v206 offset:10240
	v_mfma_f32_16x16x32_bf16 v[96:99], v[224:227], v[152:155], v[96:99]
	v_mfma_f32_16x16x32_bf16 v[100:103], v[228:231], v[152:155], v[100:103]
	v_mfma_f32_16x16x32_bf16 v[104:107], v[232:235], v[152:155], v[104:107]
	v_mfma_f32_16x16x32_bf16 v[108:111], v[236:239], v[152:155], v[108:111]
	ds_read_b128 v[152:155], v206 offset:12288
	v_mfma_f32_16x16x32_bf16 v[112:115], v[224:227], v[156:159], v[112:115]
	v_mfma_f32_16x16x32_bf16 v[116:119], v[228:231], v[156:159], v[116:119]
	v_mfma_f32_16x16x32_bf16 v[120:123], v[232:235], v[156:159], v[120:123]
	v_mfma_f32_16x16x32_bf16 v[124:127], v[236:239], v[156:159], v[124:127]
	ds_read_b128 v[156:159], v206 offset:14336
	ds_read_b128 v[224:227], v211
	ds_read_b128 v[228:231], v211 offset:2048
	ds_read_b128 v[232:235], v211 offset:4096
	ds_read_b128 v[236:239], v211 offset:6144
	s_add_u32 s22, s22, 0x80
	s_addc_u32 s23, s23, 0
	s_add_u32 s24, s24, 0x80
	s_addc_u32 s25, s25, 0
	s_add_u32 s26, s26, 1
	s_cmp_eq_u32 s26, s50
	s_cbranch_scc0 .Lgm_cadv_done5
	s_mov_b32 s26, 0
	s_add_u32 s27, s27, s30
	s_cmp_lt_u32 s27, s29
	s_cbranch_scc1 .Lgm_cadv_new5
	s_lshl_b32 s53, s50, 7
	s_sub_u32 s22, s22, s53
	s_subb_u32 s23, s23, 0
	s_sub_u32 s24, s24, s53
	s_subb_u32 s25, s25, 0
	s_branch .Lgm_cadv_done5

; #define RAWBAR() { asm volatile("s_waitcnt vmcnt(0) lgkmcnt(0)" ::: "memory"); __builtin_amdgcn_s_barrier(); }
;     ...
;   if (V != 1) GLDS(0, 0);
;   RAWBAR();
;   for (int kt = 0; kt < nk; kt += 2) {
;     if (V != 1) GLDS(kt + 1, 1);
;     if (V != 2) COMPUTE(0);
;     RAWBAR();
;     if (V != 1) if (kt + 2 < nk) GLDS(kt + 2, 0);
;     if (V != 2) COMPUTE(1);
;     RAWBAR();
.Lgm_cadv_done7:
	s_waitcnt lgkmcnt(8)
	v_mfma_f32_16x16x32_bf16 v[0:3], v[162:165], v[128:131], v[0:3]
	v_mfma_f32_16x16x32_bf16 v[4:7], v[166:169], v[128:131], v[4:7]
	v_mfma_f32_16x16x32_bf16 v[8:11], v[170:173], v[128:131], v[8:11]
	v_mfma_f32_16x16x32_bf16 v[12:15], v[174:177], v[128:131], v[12:15]
	ds_read_b128 v[128:131], v207
	v_mfma_f32_16x16x32_bf16 v[16:19], v[162:165], v[132:135], v[16:19]
	v_mfma_f32_16x16x32_bf16 v[20:23], v[166:169], v[132:135], v[20:23]
	v_mfma_f32_16x16x32_bf16 v[24:27], v[170:173], v[132:135], v[24:27]
	v_mfma_f32_16x16x32_bf16 v[28:31], v[174:177], v[132:135], v[28:31]
	ds_read_b128 v[132:135], v207 offset:2048
	v_mfma_f32_16x16x32_bf16 v[32:35], v[162:165], v[136:139], v[32:35]
	v_mfma_f32_16x16x32_bf16 v[36:39], v[166:169], v[136:139], v[36:39]
	v_mfma_f32_16x16x32_bf16 v[40:43], v[170:173], v[136:139], v[40:43]
	v_mfma_f32_16x16x32_bf16 v[44:47], v[174:177], v[136:139], v[44:47]
	ds_read_b128 v[136:139], v207 offset:4096
	v_mfma_f32_16x16x32_bf16 v[48:51], v[162:165], v[140:143], v[48:51]
	v_mfma_f32_16x16x32_bf16 v[52:55], v[166:169], v[140:143], v[52:55]
	v_mfma_f32_16x16x32_bf16 v[56:59], v[170:173], v[140:143], v[56:59]
	v_mfma_f32_16x16x32_bf16 v[60:63], v[174:177], v[140:143], v[60:63]
	ds_read_b128 v[140:143], v207 offset:6144
	s_waitcnt lgkmcnt(8)
	v_mfma_f32_16x16x32_bf16 v[64:67], v[162:165], v[144:147], v[64:67]
	v_mfma_f32_16x16x32_bf16 v[68:71], v[166:169], v[144:147], v[68:71]
	v_mfma_f32_16x16x32_bf16 v[72:75], v[170:173], v[144:147], v[72:75]
	v_mfma_f32_16x16x32_bf16 v[76:79], v[174:177], v[144:147], v[76:79]
	ds_read_b128 v[144:147], v207 offset:8192
	v_mfma_f32_16x16x32_bf16 v[80:83], v[162:165], v[148:151], v[80:83]
	v_mfma_f32_16x16x32_bf16 v[84:87], v[166:169], v[148:151], v[84:87]
	v_mfma_f32_16x16x32_bf16 v[88:91], v[170:173], v[148:151], v[88:91]
	v_mfma_f32_16x16x32_bf16 v[92:95], v[174:177], v[148:151], v[92:95]
	ds_read_b128 v[148:151], v207 offset:10240
	v_mfma_f32_16x16x32_bf16 v[96:99], v[162:165], v[152:155], v[96:99]
	v_mfma_f32_16x16x32_bf16 v[100:103], v[166:169], v[152:155], v[100:103]
	v_mfma_f32_16x16x32_bf16 v[104:107], v[170:173], v[152:155], v[104:107]
	v_mfma_f32_16x16x32_bf16 v[108:111], v[174:177], v[152:155], v[108:111]
	ds_read_b128 v[152:155], v207 offset:12288
	v_mfma_f32_16x16x32_bf16 v[112:115], v[162:165], v[156:159], v[112:115]
	v_mfma_f32_16x16x32_bf16 v[116:119], v[166:169], v[156:159], v[116:119]
	v_mfma_f32_16x16x32_bf16 v[120:123], v[170:173], v[156:159], v[120:123]
	v_mfma_f32_16x16x32_bf16 v[124:127], v[174:177], v[156:159], v[124:127]
	ds_read_b128 v[156:159], v207 offset:14336
	s_waitcnt vmcnt(0) lgkmcnt(0)
	s_barrier
	ds_read_b128 v[162:165], v208
	ds_read_b128 v[166:169], v208 offset:2048
	ds_read_b128 v[170:173], v208 offset:4096
	ds_read_b128 v[174:177], v208 offset:6144
	s_add_u32 m0, s14, 0x10000
	v_mfma_f32_16x16x32_bf16 v[0:3], v[224:227], v[128:131], v[0:3]
	global_load_lds_dwordx4 v220, s[22:23]
	v_mfma_f32_16x16x32_bf16 v[4:7], v[228:231], v[128:131], v[4:7]
	s_add_u32 m0, s14, 0x10400
	v_mfma_f32_16x16x32_bf16 v[8:11], v[232:235], v[128:131], v[8:11]
	global_load_lds_dwordx4 v221, s[22:23]
	v_mfma_f32_16x16x32_bf16 v[12:15], v[236:239], v[128:131], v[12:15]
	ds_read_b128 v[128:131], v204
	s_add_u32 m0, s14, 0x10800
	v_mfma_f32_16x16x32_bf16 v[16:19], v[224:227], v[132:135], v[16:19]
	global_load_lds_dwordx4 v222, s[22:23]
	v_mfma_f32_16x16x32_bf16 v[20:23], v[228:231], v[132:135], v[20:23]
	s_add_u32 m0, s14, 0x10c00
	v_mfma_f32_16x16x32_bf16 v[24:27], v[232:235], v[132:135], v[24:27]
	global_load_lds_dwordx4 v223, s[22:23]
	v_mfma_f32_16x16x32_bf16 v[28:31], v[236:239], v[132:135], v[28:31]
	ds_read_b128 v[132:135], v204 offset:2048
	v_mfma_f32_16x16x32_bf16 v[32:35], v[224:227], v[136:139], v[32:35]
	v_mfma_f32_16x16x32_bf16 v[36:39], v[228:231], v[136:139], v[36:39]
	v_mfma_f32_16x16x32_bf16 v[40:43], v[232:235], v[136:139], v[40:43]
	v_mfma_f32_16x16x32_bf16 v[44:47], v[236:239], v[136:139], v[44:47]
	ds_read_b128 v[136:139], v204 offset:4096
	v_mfma_f32_16x16x32_bf16 v[48:51], v[224:227], v[140:143], v[48:51]
	v_mfma_f32_16x16x32_bf16 v[52:55], v[228:231], v[140:143], v[52:55]
	v_mfma_f32_16x16x32_bf16 v[56:59], v[232:235], v[140:143], v[56:59]
	v_mfma_f32_16x16x32_bf16 v[60:63], v[236:239], v[140:143], v[60:63]
	ds_read_b128 v[140:143], v204 offset:6144
	v_mfma_f32_16x16x32_bf16 v[64:67], v[224:227], v[144:147], v[64:67]
	v_mfma_f32_16x16x32_bf16 v[68:71], v[228:231], v[144:147], v[68:71]
	v_mfma_f32_16x16x32_bf16 v[72:75], v[232:235], v[144:147], v[72:75]
	v_mfma_f32_16x16x32_bf16 v[76:79], v[236:239], v[144:147], v[76:79]
	ds_read_b128 v[144:147], v204 offset:8192
	v_mfma_f32_16x16x32_bf16 v[80:83], v[224:227], v[148:151], v[80:83]
	v_mfma_f32_16x16x32_bf16 v[84:87], v[228:231], v[148:151], v[84:87]
	v_mfma_f32_16x16x32_bf16 v[88:91], v[232:235], v[148:151], v[88:91]
	v_mfma_f32_16x16x32_bf16 v[92:95], v[236:239], v[148:151], v[92:95]
	ds_read_b128 v[148:151], v204 offset:10240
	v_mfma_f32_16x16x32_bf16 v[96:99], v[224:227], v[152:155], v[96:99]
	v_mfma_f32_16x16x32_bf16 v[100:103], v[228:231], v[152:155], v[100:103]
	v_mfma_f32_16x16x32_bf16 v[104:107], v[232:235], v[152:155], v[104:107]
	v_mfma_f32_16x16x32_bf16 v[108:111], v[236:239], v[152:155], v[108:111]
	ds_read_b128 v[152:155], v204 offset:12288
	v_mfma_f32_16x16x32_bf16 v[112:115], v[224:227], v[156:159], v[112:115]
	v_mfma_f32_16x16x32_bf16 v[116:119], v[228:231], v[156:159], v[116:119]
	v_mfma_f32_16x16x32_bf16 v[120:123], v[232:235], v[156:159], v[120:123]
	v_mfma_f32_16x16x32_bf16 v[124:127], v[236:239], v[156:159], v[124:127]
	ds_read_b128 v[156:159], v204 offset:14336
	ds_read_b128 v[224:227], v209
	ds_read_b128 v[228:231], v209 offset:2048
	ds_read_b128 v[232:235], v209 offset:4096
	ds_read_b128 v[236:239], v209 offset:6144
	s_lshr_b32 s53, s28, 5
	s_and_b32 s54, s28, 31
	s_lshr_b32 s55, s53, s34
	s_lshl_b32 s56, s55, s34
	s_sub_u32 s56, s53, s56
	s_lshl_b32 s55, s55, 3
	s_add_u32 s55, s55, s31
	s_lshr_b32 s57, s54, 2
	s_add_u32 s55, s55, s57
	s_lshl_b32 s56, s56, 2
	s_and_b32 s57, s54, 3
	s_add_u32 s56, s56, s57
	s_lshl_b32 s57, s55, 8
	s_add_u32 s57, s57, s58
	s_mul_i32 s57, s57, s36
	s_add_u32 s38, s12, s57
	s_addc_u32 s39, s13, 0
	s_lshl_b32 s57, s56, 9
	s_add_u32 s57, s57, s59
	s_add_u32 s38, s38, s57
	s_addc_u32 s39, s39, 0
	s_cmp_eq_u64 s[4:5], 0
	s_cbranch_scc1 .Lgm_epi_relu
; DI int crow(int r, int hf) { return (r & 3) + 8 * (r >> 2) + 4 * hf; }
;     ...
;     gemm_tile<V>(A + (size_t)m0 * lda, lda, K / 64, nullptr, 0, 0, Wt + (size_t)n0 * ldb, ldb, smem, [&](f32x16(&acc)[2][2], int moff) {
;       const int m0_ = m0 + moff;
;       int l32_ = l32, hf_ = hf; asm volatile("" : "+v"(l32_), "+v"(hf_));
; #pragma unroll
;       for (int i = 0; i < 2; ++i)
; #pragma unroll
;         for (int j = 0; j < 2; ++j)
; #pragma unroll
;           for (int r = 0; r < 16; ++r) {
;             const int row = m0_ + wm * 64 + i * 32 + crow(r, hf_), col = n0 + wn * 64 + j * 32 + l32_;
;             float v = acc[i][j][r];
;             if (mode == 1) { v = fmaxf(v, 0.f); v = v * v; }
;             if (V == 0 || v == 123456.789f) C[(size_t)row * ldc + col] = f2bf(v);
;           }
;     });
	v_cvt_pk_bf16_f32 v240, v0, v1
	v_cvt_pk_bf16_f32 v241, v2, v3
	ds_write_b64 v178, v[240:241] offset:32768
	v_cvt_pk_bf16_f32 v242, v4, v5
	v_cvt_pk_bf16_f32 v243, v6, v7
	ds_write_b64 v179, v[242:243] offset:32768
	v_cvt_pk_bf16_f32 v244, v8, v9
	v_cvt_pk_bf16_f32 v245, v10, v11
	ds_write_b64 v180, v[244:245] offset:32768
	v_cvt_pk_bf16_f32 v246, v12, v13
	v_cvt_pk_bf16_f32 v247, v14, v15
	ds_write_b64 v181, v[246:247] offset:32768
	v_cvt_pk_bf16_f32 v240, v16, v17
	v_cvt_pk_bf16_f32 v241, v18, v19
	ds_write_b64 v178, v[240:241] offset:34816
	v_cvt_pk_bf16_f32 v242, v20, v21
	v_cvt_pk_bf16_f32 v243, v22, v23
	ds_write_b64 v179, v[242:243] offset:34816
	v_cvt_pk_bf16_f32 v244, v24, v25
	v_cvt_pk_bf16_f32 v245, v26, v27
	ds_write_b64 v180, v[244:245] offset:34816
	v_cvt_pk_bf16_f32 v246, v28, v29
	v_cvt_pk_bf16_f32 v247, v30, v31
	ds_write_b64 v181, v[246:247] offset:34816
	ds_read_b128 v[0:3], v194 offset:32768
	ds_read_b128 v[4:7], v188 offset:33792
	ds_read_b128 v[8:11], v194 offset:34816
	ds_read_b128 v[12:15], v188 offset:35840
	v_cvt_pk_bf16_f32 v240, v32, v33
	v_cvt_pk_bf16_f32 v241, v34, v35
	ds_write_b64 v178, v[240:241] offset:32768
	v_cvt_pk_bf16_f32 v242, v36, v37
	v_cvt_pk_bf16_f32 v243, v38, v39
	ds_write_b64 v179, v[242:243] offset:32768
	v_cvt_pk_bf16_f32 v244, v40, v41
	v_cvt_pk_bf16_f32 v245, v42, v43
	ds_write_b64 v180, v[244:245] offset:32768
	v_cvt_pk_bf16_f32 v246, v44, v45
	v_cvt_pk_bf16_f32 v247, v46, v47
	ds_write_b64 v181, v[246:247] offset:32768
	v_cvt_pk_bf16_f32 v240, v48, v49
	v_cvt_pk_bf16_f32 v241, v50, v51
	ds_write_b64 v178, v[240:241] offset:34816
	v_cvt_pk_bf16_f32 v242, v52, v53
	v_cvt_pk_bf16_f32 v243, v54, v55
	ds_write_b64 v179, v[242:243] offset:34816
	v_cvt_pk_bf16_f32 v244, v56, v57
	v_cvt_pk_bf16_f32 v245, v58, v59
	ds_write_b64 v180, v[244:245] offset:34816
	v_cvt_pk_bf16_f32 v246, v60, v61
	v_cvt_pk_bf16_f32 v247, v62, v63
	ds_write_b64 v181, v[246:247] offset:34816
	ds_read_b128 v[32:35], v194 offset:32768
	ds_read_b128 v[36:39], v188 offset:33792
	ds_read_b128 v[40:43], v194 offset:34816
	ds_read_b128 v[44:47], v188 offset:35840
	s_waitcnt lgkmcnt(12)
	global_store_dwordx4 v195, v[0:3], s[38:39]
	s_add_u32 s38, s38, s40
	s_addc_u32 s39, s39, 0
	global_store_dwordx4 v195, v[4:7], s[38:39]
	s_add_u32 s38, s38, s40
	s_addc_u32 s39, s39, 0
	global_store_dwordx4 v195, v[8:11], s[38:39]
	s_add_u32 s38, s38, s40
	s_addc_u32 s39, s39, 0
	global_store_dwordx4 v195, v[12:15], s[38:39]
	s_add_u32 s38, s38, s40
	s_addc_u32 s39, s39, 0
	v_cvt_pk_bf16_f32 v240, v64, v65
	v_cvt_pk_bf16_f32 v241, v66, v67
	ds_write_b64 v178, v[240:241] offset:32768
	v_cvt_pk_bf16_f32 v242, v68, v69
	v_cvt_pk_bf16_f32 v243, v70, v71
	ds_write_b64 v179, v[242:243] offset:32768
	v_cvt_pk_bf16_f32 v244, v72, v73
	v_cvt_pk_bf16_f32 v245, v74, v75
	ds_write_b64 v180, v[244:245] offset:32768
	v_cvt_pk_bf16_f32 v246, v76, v77
	v_cvt_pk_bf16_f32 v247, v78, v79
	ds_write_b64 v181, v[246:247] offset:32768
	v_cvt_pk_bf16_f32 v240, v80, v81
	v_cvt_pk_bf16_f32 v241, v82, v83
	ds_write_b64 v178, v[240:241] offset:34816
	v_cvt_pk_bf16_f32 v242, v84, v85
	v_cvt_pk_bf16_f32 v243, v86, v87
	ds_write_b64 v179, v[242:243] offset:34816
	v_cvt_pk_bf16_f32 v244, v88, v89
	v_cvt_pk_bf16_f32 v245, v90, v91
	ds_write_b64 v180, v[244:245] offset:34816
	v_cvt_pk_bf16_f32 v246, v92, v93
	v_cvt_pk_bf16_f32 v247, v94, v95
	ds_write_b64 v181, v[246:247] offset:34816
	ds_read_b128 v[64:67], v194 offset:32768
	ds_read_b128 v[68:71], v188 offset:33792
	ds_read_b128 v[72:75], v194 offset:34816
	ds_read_b128 v[76:79], v188 offset:35840
	s_waitcnt lgkmcnt(12)
	global_store_dwordx4 v195, v[32:35], s[38:39]
	s_add_u32 s38, s38, s40
	s_addc_u32 s39, s39, 0
	global_store_dwordx4 v195, v[36:39], s[38:39]
	s_add_u32 s38, s38, s40
	s_addc_u32 s39, s39, 0
	global_store_dwordx4 v195, v[40:43], s[38:39]
	s_add_u32 s38, s38, s40
	s_addc_u32 s39, s39, 0
	global_store_dwordx4 v195, v[44:47], s[38:39]
	s_add_u32 s38, s38, s40
	s_addc_u32 s39, s39, 0
	v_cvt_pk_bf16_f32 v240, v96, v97
	v_cvt_pk_bf16_f32 v241, v98, v99
	ds_write_b64 v178, v[240:241] offset:32768
	v_cvt_pk_bf16_f32 v242, v100, v101
	v_cvt_pk_bf16_f32 v243, v102, v103
	ds_write_b64 v179, v[242:243] offset:32768
	v_cvt_pk_bf16_f32 v244, v104, v105
	v_cvt_pk_bf16_f32 v245, v106, v107
	ds_write_b64 v180, v[244:245] offset:32768
	v_cvt_pk_bf16_f32 v246, v108, v109
	v_cvt_pk_bf16_f32 v247, v110, v111
	ds_write_b64 v181, v[246:247] offset:32768
	v_cvt_pk_bf16_f32 v240, v112, v113
	v_cvt_pk_bf16_f32 v241, v114, v115
	ds_write_b64 v178, v[240:241] offset:34816
	v_cvt_pk_bf16_f32 v242, v116, v117
	v_cvt_pk_bf16_f32 v243, v118, v119
	ds_write_b64 v179, v[242:243] offset:34816
	v_cvt_pk_bf16_f32 v244, v120, v121
	v_cvt_pk_bf16_f32 v245, v122, v123
	ds_write_b64 v180, v[244:245] offset:34816
	v_cvt_pk_bf16_f32 v246, v124, v125
	v_cvt_pk_bf16_f32 v247, v126, v127
	ds_write_b64 v181, v[246:247] offset:34816
	ds_read_b128 v[96:99], v194 offset:32768
	ds_read_b128 v[100:103], v188 offset:33792
	ds_read_b128 v[104:107], v194 offset:34816
	ds_read_b128 v[108:111], v188 offset:35840
	s_waitcnt lgkmcnt(12)
	global_store_dwordx4 v195, v[64:67], s[38:39]
	s_add_u32 s38, s38, s40
	s_addc_u32 s39, s39, 0
	global_store_dwordx4 v195, v[68:71], s[38:39]
	s_add_u32 s38, s38, s40
	s_addc_u32 s39, s39, 0
	global_store_dwordx4 v195, v[72:75], s[38:39]
	s_add_u32 s38, s38, s40
	s_addc_u32 s39, s39, 0
	global_store_dwordx4 v195, v[76:79], s[38:39]
	s_add_u32 s38, s38, s40
	s_addc_u32 s39, s39, 0
	s_waitcnt lgkmcnt(0)
	global_store_dwordx4 v195, v[96:99], s[38:39]
	s_add_u32 s38, s38, s40
	s_addc_u32 s39, s39, 0
	global_store_dwordx4 v195, v[100:103], s[38:39]
	s_add_u32 s38, s38, s40
	s_addc_u32 s39, s39, 0
	global_store_dwordx4 v195, v[104:107], s[38:39]
	s_add_u32 s38, s38, s40
	s_addc_u32 s39, s39, 0
	global_store_dwordx4 v195, v[108:111], s[38:39]
	s_branch .Lgm_epi_done
; DI int crow(int r, int hf) { return (r & 3) + 8 * (r >> 2) + 4 * hf; }
;     ...
;     gemm_tile<V>(A + (size_t)m0 * lda, lda, K / 64, nullptr, 0, 0, Wt + (size_t)n0 * ldb, ldb, smem, [&](f32x16(&acc)[2][2], int moff) {
;       const int m0_ = m0 + moff;
;       int l32_ = l32, hf_ = hf; asm volatile("" : "+v"(l32_), "+v"(hf_));
; #pragma unroll
;       for (int i = 0; i < 2; ++i)
; #pragma unroll
;         for (int j = 0; j < 2; ++j)
; #pragma unroll
;           for (int r = 0; r < 16; ++r) {
;             const int row = m0_ + wm * 64 + i * 32 + crow(r, hf_), col = n0 + wn * 64 + j * 32 + l32_;
;             float v = acc[i][j][r];
;             if (mode == 1) { v = fmaxf(v, 0.f); v = v * v; }
;             if (V == 0 || v == 123456.789f) C[(size_t)row * ldc + col] = f2bf(v);
;           }
;     });
.Lgm_epi_relu:
	v_max_f32_e32 v0, 0, v0
	v_max_f32_e32 v1, 0, v1
	v_max_f32_e32 v2, 0, v2
	v_max_f32_e32 v3, 0, v3
	v_mul_f32_e32 v0, v0, v0
	v_mul_f32_e32 v1, v1, v1
	v_mul_f32_e32 v2, v2, v2
	v_mul_f32_e32 v3, v3, v3
	v_cvt_pk_bf16_f32 v240, v0, v1
	v_cvt_pk_bf16_f32 v241, v2, v3
	ds_write_b64 v178, v[240:241] offset:32768
	v_max_f32_e32 v4, 0, v4
	v_max_f32_e32 v5, 0, v5
	v_max_f32_e32 v6, 0, v6
	v_max_f32_e32 v7, 0, v7
	v_mul_f32_e32 v4, v4, v4
	v_mul_f32_e32 v5, v5, v5
	v_mul_f32_e32 v6, v6, v6
	v_mul_f32_e32 v7, v7, v7
	v_cvt_pk_bf16_f32 v242, v4, v5
	v_cvt_pk_bf16_f32 v243, v6, v7
	ds_write_b64 v179, v[242:243] offset:32768
	v_max_f32_e32 v8, 0, v8
	v_max_f32_e32 v9, 0, v9
	v_max_f32_e32 v10, 0, v10
	v_max_f32_e32 v11, 0, v11
	v_mul_f32_e32 v8, v8, v8
	v_mul_f32_e32 v9, v9, v9
	v_mul_f32_e32 v10, v10, v10
	v_mul_f32_e32 v11, v11, v11
	v_cvt_pk_bf16_f32 v244, v8, v9
	v_cvt_pk_bf16_f32 v245, v10, v11
	ds_write_b64 v180, v[244:245] offset:32768
	v_max_f32_e32 v12, 0, v12
	v_max_f32_e32 v13, 0, v13
	v_max_f32_e32 v14, 0, v14
	v_max_f32_e32 v15, 0, v15
	v_mul_f32_e32 v12, v12, v12
	v_mul_f32_e32 v13, v13, v13
	v_mul_f32_e32 v14, v14, v14
	v_mul_f32_e32 v15, v15, v15
	v_cvt_pk_bf16_f32 v246, v12, v13
	v_cvt_pk_bf16_f32 v247, v14, v15
	ds_write_b64 v181, v[246:247] offset:32768
	v_max_f32_e32 v16, 0, v16
	v_max_f32_e32 v17, 0, v17
	v_max_f32_e32 v18, 0, v18
	v_max_f32_e32 v19, 0, v19
	v_mul_f32_e32 v16, v16, v16
	v_mul_f32_e32 v17, v17, v17
	v_mul_f32_e32 v18, v18, v18
	v_mul_f32_e32 v19, v19, v19
	v_cvt_pk_bf16_f32 v240, v16, v17
	v_cvt_pk_bf16_f32 v241, v18, v19
	ds_write_b64 v178, v[240:241] offset:34816
	v_max_f32_e32 v20, 0, v20
	v_max_f32_e32 v21, 0, v21
	v_max_f32_e32 v22, 0, v22
	v_max_f32_e32 v23, 0, v23
	v_mul_f32_e32 v20, v20, v20
	v_mul_f32_e32 v21, v21, v21
	v_mul_f32_e32 v22, v22, v22
	v_mul_f32_e32 v23, v23, v23
	v_cvt_pk_bf16_f32 v242, v20, v21
	v_cvt_pk_bf16_f32 v243, v22, v23
	ds_write_b64 v179, v[242:243] offset:34816
	v_max_f32_e32 v24, 0, v24
	v_max_f32_e32 v25, 0, v25
	v_max_f32_e32 v26, 0, v26
	v_max_f32_e32 v27, 0, v27
	v_mul_f32_e32 v24, v24, v24
	v_mul_f32_e32 v25, v25, v25
	v_mul_f32_e32 v26, v26, v26
	v_mul_f32_e32 v27, v27, v27
	v_cvt_pk_bf16_f32 v244, v24, v25
	v_cvt_pk_bf16_f32 v245, v26, v27
	ds_write_b64 v180, v[244:245] offset:34816
	v_max_f32_e32 v28, 0, v28
	v_max_f32_e32 v29, 0, v29
	v_max_f32_e32 v30, 0, v30
	v_max_f32_e32 v31, 0, v31
	v_mul_f32_e32 v28, v28, v28
	v_mul_f32_e32 v29, v29, v29
	v_mul_f32_e32 v30, v30, v30
	v_mul_f32_e32 v31, v31, v31
	v_cvt_pk_bf16_f32 v246, v28, v29
	v_cvt_pk_bf16_f32 v247, v30, v31
	ds_write_b64 v181, v[246:247] offset:34816
	ds_read_b128 v[0:3], v194 offset:32768
	ds_read_b128 v[4:7], v188 offset:33792
	ds_read_b128 v[8:11], v194 offset:34816
	ds_read_b128 v[12:15], v188 offset:35840
	v_max_f32_e32 v32, 0, v32
	v_max_f32_e32 v33, 0, v33
	v_max_f32_e32 v34, 0, v34
	v_max_f32_e32 v35, 0, v35
	v_mul_f32_e32 v32, v32, v32
	v_mul_f32_e32 v33, v33, v33
	v_mul_f32_e32 v34, v34, v34
	v_mul_f32_e32 v35, v35, v35
	v_cvt_pk_bf16_f32 v240, v32, v33
	v_cvt_pk_bf16_f32 v241, v34, v35
	ds_write_b64 v178, v[240:241] offset:32768
	v_max_f32_e32 v36, 0, v36
	v_max_f32_e32 v37, 0, v37
	v_max_f32_e32 v38, 0, v38
	v_max_f32_e32 v39, 0, v39
	v_mul_f32_e32 v36, v36, v36
	v_mul_f32_e32 v37, v37, v37
	v_mul_f32_e32 v38, v38, v38
	v_mul_f32_e32 v39, v39, v39
	v_cvt_pk_bf16_f32 v242, v36, v37
	v_cvt_pk_bf16_f32 v243, v38, v39
	ds_write_b64 v179, v[242:243] offset:32768
	v_max_f32_e32 v40, 0, v40
	v_max_f32_e32 v41, 0, v41
	v_max_f32_e32 v42, 0, v42
	v_max_f32_e32 v43, 0, v43
	v_mul_f32_e32 v40, v40, v40
	v_mul_f32_e32 v41, v41, v41
	v_mul_f32_e32 v42, v42, v42
	v_mul_f32_e32 v43, v43, v43
	v_cvt_pk_bf16_f32 v244, v40, v41
	v_cvt_pk_bf16_f32 v245, v42, v43
	ds_write_b64 v180, v[244:245] offset:32768
	v_max_f32_e32 v44, 0, v44
	v_max_f32_e32 v45, 0, v45
	v_max_f32_e32 v46, 0, v46
	v_max_f32_e32 v47, 0, v47
	v_mul_f32_e32 v44, v44, v44
	v_mul_f32_e32 v45, v45, v45
	v_mul_f32_e32 v46, v46, v46
	v_mul_f32_e32 v47, v47, v47
	v_cvt_pk_bf16_f32 v246, v44, v45
	v_cvt_pk_bf16_f32 v247, v46, v47
	ds_write_b64 v181, v[246:247] offset:32768
	v_max_f32_e32 v48, 0, v48
	v_max_f32_e32 v49, 0, v49
	v_max_f32_e32 v50, 0, v50
	v_max_f32_e32 v51, 0, v51
	v_mul_f32_e32 v48, v48, v48
	v_mul_f32_e32 v49, v49, v49
	v_mul_f32_e32 v50, v50, v50
	v_mul_f32_e32 v51, v51, v51
	v_cvt_pk_bf16_f32 v240, v48, v49
	v_cvt_pk_bf16_f32 v241, v50, v51
	ds_write_b64 v178, v[240:241] offset:34816
	v_max_f32_e32 v52, 0, v52
	v_max_f32_e32 v53, 0, v53
	v_max_f32_e32 v54, 0, v54
	v_max_f32_e32 v55, 0, v55
	v_mul_f32_e32 v52, v52, v52
	v_mul_f32_e32 v53, v53, v53
	v_mul_f32_e32 v54, v54, v54
	v_mul_f32_e32 v55, v55, v55
	v_cvt_pk_bf16_f32 v242, v52, v53
	v_cvt_pk_bf16_f32 v243, v54, v55
	ds_write_b64 v179, v[242:243] offset:34816
	v_max_f32_e32 v56, 0, v56
	v_max_f32_e32 v57, 0, v57
	v_max_f32_e32 v58, 0, v58
	v_max_f32_e32 v59, 0, v59
	v_mul_f32_e32 v56, v56, v56
	v_mul_f32_e32 v57, v57, v57
	v_mul_f32_e32 v58, v58, v58
	v_mul_f32_e32 v59, v59, v59
	v_cvt_pk_bf16_f32 v244, v56, v57
	v_cvt_pk_bf16_f32 v245, v58, v59
	ds_write_b64 v180, v[244:245] offset:34816
	v_max_f32_e32 v60, 0, v60
	v_max_f32_e32 v61, 0, v61
	v_max_f32_e32 v62, 0, v62
	v_max_f32_e32 v63, 0, v63
	v_mul_f32_e32 v60, v60, v60
	v_mul_f32_e32 v61, v61, v61
	v_mul_f32_e32 v62, v62, v62
	v_mul_f32_e32 v63, v63, v63
	v_cvt_pk_bf16_f32 v246, v60, v61
	v_cvt_pk_bf16_f32 v247, v62, v63
	ds_write_b64 v181, v[246:247] offset:34816
	ds_read_b128 v[32:35], v194 offset:32768
	ds_read_b128 v[36:39], v188 offset:33792
	ds_read_b128 v[40:43], v194 offset:34816
	ds_read_b128 v[44:47], v188 offset:35840
	s_waitcnt lgkmcnt(12)
; DI int crow(int r, int hf) { return (r & 3) + 8 * (r >> 2) + 4 * hf; }
;     ...
;     gemm_tile<V>(A + (size_t)m0 * lda, lda, K / 64, nullptr, 0, 0, Wt + (size_t)n0 * ldb, ldb, smem, [&](f32x16(&acc)[2][2], int moff) {
;       const int m0_ = m0 + moff;
;       int l32_ = l32, hf_ = hf; asm volatile("" : "+v"(l32_), "+v"(hf_));
; #pragma unroll
;       for (int i = 0; i < 2; ++i)
; #pragma unroll
;         for (int j = 0; j < 2; ++j)
; #pragma unroll
;           for (int r = 0; r < 16; ++r) {
;             const int row = m0_ + wm * 64 + i * 32 + crow(r, hf_), col = n0 + wn * 64 + j * 32 + l32_;
;             float v = acc[i][j][r];
;             if (mode == 1) { v = fmaxf(v, 0.f); v = v * v; }
;             if (V == 0 || v == 123456.789f) C[(size_t)row * ldc + col] = f2bf(v);
;           }
;     });
	global_store_dwordx4 v195, v[0:3], s[38:39] nt
	s_add_u32 s38, s38, s40
	s_addc_u32 s39, s39, 0
	global_store_dwordx4 v195, v[4:7], s[38:39] nt
	s_add_u32 s38, s38, s40
	s_addc_u32 s39, s39, 0
	global_store_dwordx4 v195, v[8:11], s[38:39] nt
	s_add_u32 s38, s38, s40
	s_addc_u32 s39, s39, 0
	global_store_dwordx4 v195, v[12:15], s[38:39] nt
	s_add_u32 s38, s38, s40
	s_addc_u32 s39, s39, 0
	v_max_f32_e32 v64, 0, v64
	v_max_f32_e32 v65, 0, v65
	v_max_f32_e32 v66, 0, v66
	v_max_f32_e32 v67, 0, v67
	v_mul_f32_e32 v64, v64, v64
	v_mul_f32_e32 v65, v65, v65
	v_mul_f32_e32 v66, v66, v66
	v_mul_f32_e32 v67, v67, v67
	v_cvt_pk_bf16_f32 v240, v64, v65
	v_cvt_pk_bf16_f32 v241, v66, v67
	ds_write_b64 v178, v[240:241] offset:32768
	v_max_f32_e32 v68, 0, v68
	v_max_f32_e32 v69, 0, v69
	v_max_f32_e32 v70, 0, v70
	v_max_f32_e32 v71, 0, v71
	v_mul_f32_e32 v68, v68, v68
	v_mul_f32_e32 v69, v69, v69
	v_mul_f32_e32 v70, v70, v70
	v_mul_f32_e32 v71, v71, v71
	v_cvt_pk_bf16_f32 v242, v68, v69
	v_cvt_pk_bf16_f32 v243, v70, v71
	ds_write_b64 v179, v[242:243] offset:32768
	v_max_f32_e32 v72, 0, v72
	v_max_f32_e32 v73, 0, v73
	v_max_f32_e32 v74, 0, v74
	v_max_f32_e32 v75, 0, v75
	v_mul_f32_e32 v72, v72, v72
	v_mul_f32_e32 v73, v73, v73
	v_mul_f32_e32 v74, v74, v74
	v_mul_f32_e32 v75, v75, v75
	v_cvt_pk_bf16_f32 v244, v72, v73
	v_cvt_pk_bf16_f32 v245, v74, v75
	ds_write_b64 v180, v[244:245] offset:32768
	v_max_f32_e32 v76, 0, v76
	v_max_f32_e32 v77, 0, v77
	v_max_f32_e32 v78, 0, v78
	v_max_f32_e32 v79, 0, v79
	v_mul_f32_e32 v76, v76, v76
	v_mul_f32_e32 v77, v77, v77
	v_mul_f32_e32 v78, v78, v78
	v_mul_f32_e32 v79, v79, v79
	v_cvt_pk_bf16_f32 v246, v76, v77
	v_cvt_pk_bf16_f32 v247, v78, v79
	ds_write_b64 v181, v[246:247] offset:32768
	v_max_f32_e32 v80, 0, v80
	v_max_f32_e32 v81, 0, v81
	v_max_f32_e32 v82, 0, v82
	v_max_f32_e32 v83, 0, v83
	v_mul_f32_e32 v80, v80, v80
	v_mul_f32_e32 v81, v81, v81
	v_mul_f32_e32 v82, v82, v82
	v_mul_f32_e32 v83, v83, v83
	v_cvt_pk_bf16_f32 v240, v80, v81
	v_cvt_pk_bf16_f32 v241, v82, v83
	ds_write_b64 v178, v[240:241] offset:34816
	v_max_f32_e32 v84, 0, v84
	v_max_f32_e32 v85, 0, v85
	v_max_f32_e32 v86, 0, v86
	v_max_f32_e32 v87, 0, v87
	v_mul_f32_e32 v84, v84, v84
	v_mul_f32_e32 v85, v85, v85
	v_mul_f32_e32 v86, v86, v86
	v_mul_f32_e32 v87, v87, v87
	v_cvt_pk_bf16_f32 v242, v84, v85
	v_cvt_pk_bf16_f32 v243, v86, v87
	ds_write_b64 v179, v[242:243] offset:34816
	v_max_f32_e32 v88, 0, v88
	v_max_f32_e32 v89, 0, v89
	v_max_f32_e32 v90, 0, v90
	v_max_f32_e32 v91, 0, v91
	v_mul_f32_e32 v88, v88, v88
	v_mul_f32_e32 v89, v89, v89
	v_mul_f32_e32 v90, v90, v90
	v_mul_f32_e32 v91, v91, v91
	v_cvt_pk_bf16_f32 v244, v88, v89
	v_cvt_pk_bf16_f32 v245, v90, v91
	ds_write_b64 v180, v[244:245] offset:34816
	v_max_f32_e32 v92, 0, v92
	v_max_f32_e32 v93, 0, v93
	v_max_f32_e32 v94, 0, v94
	v_max_f32_e32 v95, 0, v95
	v_mul_f32_e32 v92, v92, v92
	v_mul_f32_e32 v93, v93, v93
	v_mul_f32_e32 v94, v94, v94
	v_mul_f32_e32 v95, v95, v95
	v_cvt_pk_bf16_f32 v246, v92, v93
	v_cvt_pk_bf16_f32 v247, v94, v95
	ds_write_b64 v181, v[246:247] offset:34816
	ds_read_b128 v[64:67], v194 offset:32768
	ds_read_b128 v[68:71], v188 offset:33792
	ds_read_b128 v[72:75], v194 offset:34816
	ds_read_b128 v[76:79], v188 offset:35840
	s_waitcnt lgkmcnt(12)
; DI int crow(int r, int hf) { return (r & 3) + 8 * (r >> 2) + 4 * hf; }
;     ...
;     gemm_tile<V>(A + (size_t)m0 * lda, lda, K / 64, nullptr, 0, 0, Wt + (size_t)n0 * ldb, ldb, smem, [&](f32x16(&acc)[2][2], int moff) {
;       const int m0_ = m0 + moff;
;       int l32_ = l32, hf_ = hf; asm volatile("" : "+v"(l32_), "+v"(hf_));
; #pragma unroll
;       for (int i = 0; i < 2; ++i)
; #pragma unroll
;         for (int j = 0; j < 2; ++j)
; #pragma unroll
;           for (int r = 0; r < 16; ++r) {
;             const int row = m0_ + wm * 64 + i * 32 + crow(r, hf_), col = n0 + wn * 64 + j * 32 + l32_;
;             float v = acc[i][j][r];
;             if (mode == 1) { v = fmaxf(v, 0.f); v = v * v; }
;             if (V == 0 || v == 123456.789f) C[(size_t)row * ldc + col] = f2bf(v);
;           }
;     });
	global_store_dwordx4 v195, v[32:35], s[38:39] nt
	s_add_u32 s38, s38, s40
	s_addc_u32 s39, s39, 0
	global_store_dwordx4 v195, v[36:39], s[38:39] nt
	s_add_u32 s38, s38, s40
	s_addc_u32 s39, s39, 0
	global_store_dwordx4 v195, v[40:43], s[38:39] nt
	s_add_u32 s38, s38, s40
	s_addc_u32 s39, s39, 0
	global_store_dwordx4 v195, v[44:47], s[38:39] nt
	s_add_u32 s38, s38, s40
	s_addc_u32 s39, s39, 0
	v_max_f32_e32 v96, 0, v96
	v_max_f32_e32 v97, 0, v97
	v_max_f32_e32 v98, 0, v98
	v_max_f32_e32 v99, 0, v99
	v_mul_f32_e32 v96, v96, v96
	v_mul_f32_e32 v97, v97, v97
	v_mul_f32_e32 v98, v98, v98
	v_mul_f32_e32 v99, v99, v99
	v_cvt_pk_bf16_f32 v240, v96, v97
	v_cvt_pk_bf16_f32 v241, v98, v99
	ds_write_b64 v178, v[240:241] offset:32768
	v_max_f32_e32 v100, 0, v100
	v_max_f32_e32 v101, 0, v101
	v_max_f32_e32 v102, 0, v102
	v_max_f32_e32 v103, 0, v103
	v_mul_f32_e32 v100, v100, v100
	v_mul_f32_e32 v101, v101, v101
	v_mul_f32_e32 v102, v102, v102
	v_mul_f32_e32 v103, v103, v103
	v_cvt_pk_bf16_f32 v242, v100, v101
	v_cvt_pk_bf16_f32 v243, v102, v103
	ds_write_b64 v179, v[242:243] offset:32768
	v_max_f32_e32 v104, 0, v104
	v_max_f32_e32 v105, 0, v105
	v_max_f32_e32 v106, 0, v106
	v_max_f32_e32 v107, 0, v107
	v_mul_f32_e32 v104, v104, v104
	v_mul_f32_e32 v105, v105, v105
	v_mul_f32_e32 v106, v106, v106
	v_mul_f32_e32 v107, v107, v107
	v_cvt_pk_bf16_f32 v244, v104, v105
	v_cvt_pk_bf16_f32 v245, v106, v107
	ds_write_b64 v180, v[244:245] offset:32768
	v_max_f32_e32 v108, 0, v108
	v_max_f32_e32 v109, 0, v109
	v_max_f32_e32 v110, 0, v110
	v_max_f32_e32 v111, 0, v111
	v_mul_f32_e32 v108, v108, v108
	v_mul_f32_e32 v109, v109, v109
	v_mul_f32_e32 v110, v110, v110
	v_mul_f32_e32 v111, v111, v111
	v_cvt_pk_bf16_f32 v246, v108, v109
	v_cvt_pk_bf16_f32 v247, v110, v111
	ds_write_b64 v181, v[246:247] offset:32768
	v_max_f32_e32 v112, 0, v112
	v_max_f32_e32 v113, 0, v113
	v_max_f32_e32 v114, 0, v114
	v_max_f32_e32 v115, 0, v115
	v_mul_f32_e32 v112, v112, v112
	v_mul_f32_e32 v113, v113, v113
	v_mul_f32_e32 v114, v114, v114
	v_mul_f32_e32 v115, v115, v115
	v_cvt_pk_bf16_f32 v240, v112, v113
	v_cvt_pk_bf16_f32 v241, v114, v115
	ds_write_b64 v178, v[240:241] offset:34816
	v_max_f32_e32 v116, 0, v116
	v_max_f32_e32 v117, 0, v117
	v_max_f32_e32 v118, 0, v118
	v_max_f32_e32 v119, 0, v119
	v_mul_f32_e32 v116, v116, v116
	v_mul_f32_e32 v117, v117, v117
	v_mul_f32_e32 v118, v118, v118
	v_mul_f32_e32 v119, v119, v119
	v_cvt_pk_bf16_f32 v242, v116, v117
	v_cvt_pk_bf16_f32 v243, v118, v119
	ds_write_b64 v179, v[242:243] offset:34816
	v_max_f32_e32 v120, 0, v120
	v_max_f32_e32 v121, 0, v121
	v_max_f32_e32 v122, 0, v122
	v_max_f32_e32 v123, 0, v123
	v_mul_f32_e32 v120, v120, v120
	v_mul_f32_e32 v121, v121, v121
	v_mul_f32_e32 v122, v122, v122
	v_mul_f32_e32 v123, v123, v123
	v_cvt_pk_bf16_f32 v244, v120, v121
	v_cvt_pk_bf16_f32 v245, v122, v123
	ds_write_b64 v180, v[244:245] offset:34816
	v_max_f32_e32 v124, 0, v124
	v_max_f32_e32 v125, 0, v125
	v_max_f32_e32 v126, 0, v126
	v_max_f32_e32 v127, 0, v127
	v_mul_f32_e32 v124, v124, v124
	v_mul_f32_e32 v125, v125, v125
	v_mul_f32_e32 v126, v126, v126
	v_mul_f32_e32 v127, v127, v127
	v_cvt_pk_bf16_f32 v246, v124, v125
	v_cvt_pk_bf16_f32 v247, v126, v127
	ds_write_b64 v181, v[246:247] offset:34816
	ds_read_b128 v[96:99], v194 offset:32768
	ds_read_b128 v[100:103], v188 offset:33792
	ds_read_b128 v[104:107], v194 offset:34816
	ds_read_b128 v[108:111], v188 offset:35840
	s_waitcnt lgkmcnt(12)
	global_store_dwordx4 v195, v[64:67], s[38:39] nt
	s_add_u32 s38, s38, s40
	s_addc_u32 s39, s39, 0
	global_store_dwordx4 v195, v[68:71], s[38:39] nt
	s_add_u32 s38, s38, s40
	s_addc_u32 s39, s39, 0
	global_store_dwordx4 v195, v[72:75], s[38:39] nt
	s_add_u32 s38, s38, s40
	s_addc_u32 s39, s39, 0
	global_store_dwordx4 v195, v[76:79], s[38:39] nt
	s_add_u32 s38, s38, s40
	s_addc_u32 s39, s39, 0
	s_waitcnt lgkmcnt(0)
	global_store_dwordx4 v195, v[96:99], s[38:39] nt
	s_add_u32 s38, s38, s40
	s_addc_u32 s39, s39, 0
	global_store_dwordx4 v195, v[100:103], s[38:39] nt
	s_add_u32 s38, s38, s40
	s_addc_u32 s39, s39, 0
	global_store_dwordx4 v195, v[104:107], s[38:39] nt
	s_add_u32 s38, s38, s40
	s_addc_u32 s39, s39, 0
	global_store_dwordx4 v195, v[108:111], s[38:39] nt
